# speedup vs baseline: 1.0077x; 1.0077x over previous
.LBB0_332:
	v_max_f32_e32 v3, v51, v51
	v_max_f32_e32 v4, v50, v50
	v_max_f32_e32 v3, v4, v3
	v_max3_f32 v3, v3, v52, v53
	v_max3_f32 v3, v3, v54, v55
	v_max3_f32 v3, v3, v56, v57
	v_max3_f32 v3, v3, v58, v59
	v_max3_f32 v3, v3, v60, v61
	v_max3_f32 v3, v3, v62, v63
	v_max3_f32 v3, v3, v64, v65
	v_max3_f32 v3, v3, v66, v67
	v_max3_f32 v3, v3, v68, v69
	v_max3_f32 v3, v3, v70, v71
	v_max3_f32 v3, v3, v72, v73
	v_max3_f32 v3, v3, v74, v75
	v_max3_f32 v3, v3, v76, v77
	v_max3_f32 v3, v3, v78, v79
	v_max3_f32 v3, v3, v80, v81
	v_mov_b32_e32 v4, v3
	s_nop 1
	v_permlane32_swap_b32_e32 v3, v4
	v_max_f32_e32 v4, v4, v4
	v_max_f32_e32 v3, v3, v3
	v_max_f32_e32 v3, v3, v4
	v_sub_f32_e32 v4, v3, v153
	v_mul_f32_e32 v4, 0x3db504f3, v4
	v_cmp_ge_f32_e32 vcc, s96, v4
	s_cmp_eq_u64 vcc, exec
	s_cselect_b64 s[8:9], -1, 0
	s_add_i32 s10, s74, 1
	s_cmp_ge_u32 s10, s33
	s_cselect_b64 s[10:11], -1, 0
	s_add_i32 s12, s73, 1
	v_max_f32_e32 v4, v153, v153
	s_cmp_gt_u32 s12, s1
	v_max_f32_e32 v155, v4, v3
	s_cselect_b64 s[12:13], -1, 0
	v_cndmask_b32_e64 v154, v155, v153, s[8:9]
	s_or_b64 s[12:13], s[10:11], s[12:13]
	s_mov_b64 s[10:11], -1
	s_and_b64 vcc, exec, s[12:13]
	v_mul_f32_e32 v3, 0xbe0293ee, v154
	s_cbranch_vccnz .LBB0_334
	s_and_b32 s10, s4, 0x4000
	s_nop 0
	v_or_b32_e32 v12, s10, v140
	v_add_u32_e32 v16, v12, v147
	v_add_u32_e32 v17, v12, v148
	v_add_u32_e32 v114, v12, v141
	v_add_u32_e32 v115, v12, v142
	v_add_u32_e32 v116, v12, v143
	v_add_u32_e32 v117, v12, v144
	v_add_u32_e32 v118, v12, v145
	ds_read_b128 v[4:7], v16
	v_add_u32_e32 v119, v12, v146
	ds_read_b128 v[8:11], v17
	v_fmamk_f32 v120, v54, 0x3e0293ee, v3
	v_fmamk_f32 v121, v55, 0x3e0293ee, v3
	v_fmamk_f32 v122, v57, 0x3e0293ee, v3
	v_fmamk_f32 v123, v58, 0x3e0293ee, v3
	v_fmamk_f32 v124, v59, 0x3e0293ee, v3
	v_fmamk_f32 v125, v60, 0x3e0293ee, v3
	v_fmamk_f32 v126, v61, 0x3e0293ee, v3
	ds_read_b128 v[12:15], v114
	s_waitcnt lgkmcnt(0)
	v_mfma_f32_32x32x16_bf16 v[34:49], v[12:15], v[82:85], 0
	v_fmamk_f32 v127, v62, 0x3e0293ee, v3
	v_fmamk_f32 v128, v63, 0x3e0293ee, v3
	v_fmamk_f32 v129, v64, 0x3e0293ee, v3
	v_fmamk_f32 v156, v65, 0x3e0293ee, v3
	v_fmamk_f32 v157, v66, 0x3e0293ee, v3
	v_fmamk_f32 v158, v67, 0x3e0293ee, v3
	v_fmamk_f32 v159, v68, 0x3e0293ee, v3
	v_fmamk_f32 v160, v69, 0x3e0293ee, v3
	ds_read_b128 v[12:15], v115
	s_waitcnt lgkmcnt(0)
	v_mfma_f32_32x32x16_bf16 v[34:49], v[12:15], v[86:89], v[34:49]
	v_fmamk_f32 v161, v70, 0x3e0293ee, v3
	v_fmamk_f32 v162, v71, 0x3e0293ee, v3
	ds_read_b128 v[12:15], v116
	v_exp_f32_e32 v120, v120
	v_exp_f32_e32 v121, v121
	v_exp_f32_e32 v122, v122
	v_exp_f32_e32 v123, v123
	s_waitcnt lgkmcnt(0)
	v_mfma_f32_32x32x16_bf16 v[34:49], v[12:15], v[90:93], v[34:49]
	ds_read_b128 v[12:15], v117
	v_exp_f32_e32 v124, v124
	v_exp_f32_e32 v125, v125
	v_exp_f32_e32 v126, v126
	v_exp_f32_e32 v127, v127
	v_exp_f32_e32 v128, v128
	v_exp_f32_e32 v129, v129
	s_waitcnt lgkmcnt(0)
	v_mfma_f32_32x32x16_bf16 v[34:49], v[12:15], v[94:97], v[34:49]
	ds_read_b128 v[12:15], v118
	v_exp_f32_e32 v172, v157
	v_exp_f32_e32 v158, v158
	v_exp_f32_e32 v159, v159
	v_exp_f32_e32 v160, v160
	v_exp_f32_e32 v161, v161
	v_exp_f32_e32 v162, v162
	s_waitcnt lgkmcnt(0)
	v_mfma_f32_32x32x16_bf16 v[34:49], v[12:15], v[98:101], v[34:49]
	ds_read_b128 v[12:15], v119
	s_mov_b64 s[10:11], 0
	s_waitcnt lgkmcnt(0)
	v_mfma_f32_32x32x16_bf16 v[34:49], v[12:15], v[102:105], v[34:49]
	v_fmamk_f32 v12, v50, 0x3e0293ee, v3
	v_fmamk_f32 v13, v51, 0x3e0293ee, v3
	v_fmamk_f32 v14, v52, 0x3e0293ee, v3
	v_fmamk_f32 v15, v53, 0x3e0293ee, v3
	v_exp_f32_e32 v12, v12
	v_exp_f32_e32 v13, v13
	v_exp_f32_e32 v14, v14
	v_mfma_f32_32x32x16_bf16 v[34:49], v[4:7], v[106:109], v[34:49]
	ds_read_b128 v[4:7], v17 offset:8192
	v_exp_f32_e32 v15, v15
	v_mfma_f32_32x32x16_bf16 v[34:49], v[8:11], v[110:113], v[34:49]
	v_fmamk_f32 v17, v56, 0x3e0293ee, v3
	ds_read_b128 v[8:11], v114 offset:8192
	v_exp_f32_e32 v17, v17
	s_waitcnt lgkmcnt(0)
	v_mfma_f32_32x32x16_bf16 v[18:33], v[8:11], v[82:85], 0
	ds_read_b128 v[8:11], v115 offset:8192
	s_waitcnt lgkmcnt(0)
	v_mfma_f32_32x32x16_bf16 v[18:33], v[8:11], v[86:89], v[18:33]
	v_add_f32_e32 v8, 0, v12
	v_add_f32_e32 v8, v13, v8
	v_add_f32_e32 v8, v14, v8
	v_add_f32_e32 v8, v15, v8
	v_add_f32_e32 v8, v120, v8
	v_add_f32_e32 v171, v121, v8
	ds_read_b128 v[8:11], v116 offset:8192
	s_waitcnt lgkmcnt(0)
	v_mfma_f32_32x32x16_bf16 v[18:33], v[8:11], v[90:93], v[18:33]
	v_add_f32_e32 v8, v17, v171
	v_add_f32_e32 v8, v122, v8
	v_add_f32_e32 v8, v123, v8
	v_add_f32_e32 v8, v124, v8
	v_add_f32_e32 v8, v125, v8
	v_add_f32_e32 v8, v126, v8
	v_add_f32_e32 v8, v127, v8
	v_add_f32_e32 v116, v128, v8
	ds_read_b128 v[8:11], v117 offset:8192
	v_exp_f32_e32 v171, v156
	s_waitcnt lgkmcnt(0)
	v_mfma_f32_32x32x16_bf16 v[18:33], v[8:11], v[94:97], v[18:33]
	v_add_f32_e32 v8, v129, v116
	v_add_f32_e32 v8, v171, v8
	v_add_f32_e32 v8, v172, v8
	v_add_f32_e32 v8, v158, v8
	v_add_f32_e32 v8, v159, v8
	v_add_f32_e32 v8, v160, v8
	v_add_f32_e32 v8, v161, v8
	v_add_f32_e32 v116, v162, v8
	ds_read_b128 v[8:11], v118 offset:8192
	s_waitcnt lgkmcnt(0)
	v_mfma_f32_32x32x16_bf16 v[18:33], v[8:11], v[98:101], v[18:33]
	v_fmamk_f32 v163, v73, 0x3e0293ee, v3
	v_fmamk_f32 v164, v74, 0x3e0293ee, v3
	v_fmamk_f32 v165, v75, 0x3e0293ee, v3
	v_fmamk_f32 v166, v76, 0x3e0293ee, v3
	v_fmamk_f32 v167, v77, 0x3e0293ee, v3
	v_fmamk_f32 v168, v78, 0x3e0293ee, v3
	v_fmamk_f32 v169, v79, 0x3e0293ee, v3
	v_fmamk_f32 v114, v72, 0x3e0293ee, v3
	v_exp_f32_e32 v173, v114
	v_exp_f32_e32 v163, v163
	v_exp_f32_e32 v164, v164
	v_exp_f32_e32 v165, v165
	v_exp_f32_e32 v166, v166
	v_add_f32_e32 v8, v173, v116
	v_exp_f32_e32 v167, v167
	v_add_f32_e32 v8, v163, v8
	v_exp_f32_e32 v168, v168
	v_add_f32_e32 v8, v164, v8
	v_exp_f32_e32 v169, v169
	v_add_f32_e32 v8, v165, v8
	v_add_f32_e32 v8, v166, v8
	v_add_f32_e32 v8, v167, v8
	v_add_f32_e32 v8, v168, v8
	v_add_f32_e32 v114, v169, v8
	ds_read_b128 v[8:11], v119 offset:8192
	s_waitcnt lgkmcnt(0)
	v_mfma_f32_32x32x16_bf16 v[18:33], v[8:11], v[102:105], v[18:33]
	v_fmamk_f32 v170, v81, 0x3e0293ee, v3
	v_fmamk_f32 v115, v80, 0x3e0293ee, v3
	v_exp_f32_e32 v174, v115
	v_exp_f32_e32 v170, v170
	v_add_f32_e32 v8, v174, v114
	v_add_f32_e32 v156, v170, v8
	ds_read_b128 v[8:11], v16 offset:8192
	s_waitcnt lgkmcnt(0)
	v_mfma_f32_32x32x16_bf16 v[18:33], v[8:11], v[106:109], v[18:33]
	v_cvt_pk_bf16_f32 v114, v12, v13
	v_cvt_pk_bf16_f32 v115, v14, v15
	v_cvt_pk_bf16_f32 v116, v120, v121
	v_cvt_pk_bf16_f32 v117, v17, v122
	v_cvt_pk_bf16_f32 v118, v123, v124
	v_cvt_pk_bf16_f32 v119, v125, v126
	v_cvt_pk_bf16_f32 v120, v127, v128
	v_mfma_f32_32x32x16_bf16 v[18:33], v[4:7], v[110:113], v[18:33]
	v_cvt_pk_bf16_f32 v121, v129, v171
	v_cvt_pk_bf16_f32 v122, v172, v158
	v_cvt_pk_bf16_f32 v123, v159, v160
	v_cvt_pk_bf16_f32 v124, v161, v162
	v_cvt_pk_bf16_f32 v125, v173, v163
	v_cvt_pk_bf16_f32 v126, v164, v165
	v_cvt_pk_bf16_f32 v127, v166, v167
	v_cvt_pk_bf16_f32 v128, v168, v169
	v_cvt_pk_bf16_f32 v129, v174, v170
	s_nop 0
	v_permlane32_swap_b32_e32 v119, v121
	v_permlane32_swap_b32_e32 v122, v124
	v_permlane32_swap_b32_e32 v123, v125
	v_permlane32_swap_b32_e32 v126, v128
	v_permlane32_swap_b32_e32 v127, v129
	v_mov_b32_e32 v157, v156
	s_nop 1
	v_permlane32_swap_b32_e32 v156, v157
	v_permlane32_swap_b32_e32 v114, v116
	v_permlane32_swap_b32_e32 v115, v117
	v_permlane32_swap_b32_e32 v118, v120
.LBB0_334:
	s_andn2_b64 vcc, exec, s[10:11]
	s_cbranch_vccnz .LBB0_336
	v_fmamk_f32 v4, v50, 0x3e0293ee, v3
	v_fmamk_f32 v5, v51, 0x3e0293ee, v3
	v_exp_f32_e32 v4, v4
	v_fmamk_f32 v6, v52, 0x3e0293ee, v3
	v_exp_f32_e32 v5, v5
	v_fmamk_f32 v7, v53, 0x3e0293ee, v3
	v_exp_f32_e32 v6, v6
	v_fmamk_f32 v8, v54, 0x3e0293ee, v3
	v_exp_f32_e32 v7, v7
	v_fmamk_f32 v9, v55, 0x3e0293ee, v3
	v_exp_f32_e32 v8, v8
	v_add_f32_e32 v35, 0, v4
	v_fmamk_f32 v10, v56, 0x3e0293ee, v3
	v_exp_f32_e32 v9, v9
	v_add_f32_e32 v35, v5, v35
	v_fmamk_f32 v11, v57, 0x3e0293ee, v3
	v_exp_f32_e32 v10, v10
	v_add_f32_e32 v35, v6, v35
	v_fmamk_f32 v12, v58, 0x3e0293ee, v3
	v_exp_f32_e32 v11, v11
	v_add_f32_e32 v35, v7, v35
	v_fmamk_f32 v13, v59, 0x3e0293ee, v3
	v_exp_f32_e32 v12, v12
	v_add_f32_e32 v35, v8, v35
	v_fmamk_f32 v14, v60, 0x3e0293ee, v3
	v_exp_f32_e32 v13, v13
	v_add_f32_e32 v35, v9, v35
	v_fmamk_f32 v15, v61, 0x3e0293ee, v3
	v_exp_f32_e32 v14, v14
	v_add_f32_e32 v35, v10, v35
	v_fmamk_f32 v16, v62, 0x3e0293ee, v3
	v_exp_f32_e32 v15, v15
	v_add_f32_e32 v35, v11, v35
	v_fmamk_f32 v17, v63, 0x3e0293ee, v3
	v_exp_f32_e32 v16, v16
	v_add_f32_e32 v35, v12, v35
	v_fmamk_f32 v18, v64, 0x3e0293ee, v3
	v_exp_f32_e32 v17, v17
	v_add_f32_e32 v35, v13, v35
	v_fmamk_f32 v19, v65, 0x3e0293ee, v3
	v_exp_f32_e32 v18, v18
	v_add_f32_e32 v35, v14, v35
	v_fmamk_f32 v20, v66, 0x3e0293ee, v3
	v_exp_f32_e32 v19, v19
	v_add_f32_e32 v35, v15, v35
	v_fmamk_f32 v21, v67, 0x3e0293ee, v3
	v_exp_f32_e32 v20, v20
	v_add_f32_e32 v35, v16, v35
	v_fmamk_f32 v22, v68, 0x3e0293ee, v3
	v_exp_f32_e32 v21, v21
	v_add_f32_e32 v35, v17, v35
	v_fmamk_f32 v23, v69, 0x3e0293ee, v3
	v_exp_f32_e32 v22, v22
	v_add_f32_e32 v35, v18, v35
	v_fmamk_f32 v24, v70, 0x3e0293ee, v3
	v_exp_f32_e32 v23, v23
	v_add_f32_e32 v35, v19, v35
	v_fmamk_f32 v25, v71, 0x3e0293ee, v3
	v_exp_f32_e32 v24, v24
	v_add_f32_e32 v35, v20, v35
	v_fmamk_f32 v26, v72, 0x3e0293ee, v3
	v_exp_f32_e32 v25, v25
	v_add_f32_e32 v35, v21, v35
	v_fmamk_f32 v27, v73, 0x3e0293ee, v3
	v_exp_f32_e32 v26, v26
	v_add_f32_e32 v35, v22, v35
	v_fmamk_f32 v28, v74, 0x3e0293ee, v3
	v_exp_f32_e32 v27, v27
	v_add_f32_e32 v35, v23, v35
	v_fmamk_f32 v29, v75, 0x3e0293ee, v3
	v_exp_f32_e32 v28, v28
	v_add_f32_e32 v35, v24, v35
	v_fmamk_f32 v30, v76, 0x3e0293ee, v3
	v_exp_f32_e32 v29, v29
	v_add_f32_e32 v35, v25, v35
	v_fmamk_f32 v31, v77, 0x3e0293ee, v3
	v_exp_f32_e32 v30, v30
	v_add_f32_e32 v35, v26, v35
	v_fmamk_f32 v32, v78, 0x3e0293ee, v3
	v_exp_f32_e32 v31, v31
	v_add_f32_e32 v35, v27, v35
	v_fmamk_f32 v33, v79, 0x3e0293ee, v3
	v_exp_f32_e32 v32, v32
	v_add_f32_e32 v35, v28, v35
	v_fmamk_f32 v34, v80, 0x3e0293ee, v3
	v_exp_f32_e32 v33, v33
	v_add_f32_e32 v35, v29, v35
	v_fmac_f32_e32 v3, 0x3e0293ee, v81
	v_exp_f32_e32 v34, v34
	v_add_f32_e32 v35, v30, v35
	v_exp_f32_e32 v3, v3
	v_add_f32_e32 v35, v31, v35
	v_add_f32_e32 v35, v32, v35
	v_add_f32_e32 v35, v33, v35
	v_add_f32_e32 v35, v34, v35
	v_add_f32_e32 v156, v3, v35
	v_cvt_pk_bf16_f32 v114, v4, v5
	v_cvt_pk_bf16_f32 v115, v6, v7
	v_cvt_pk_bf16_f32 v116, v8, v9
	v_cvt_pk_bf16_f32 v117, v10, v11
	v_cvt_pk_bf16_f32 v118, v12, v13
	v_cvt_pk_bf16_f32 v119, v14, v15
	v_cvt_pk_bf16_f32 v120, v16, v17
	v_mov_b32_e32 v16, v2
	v_mov_b32_e32 v17, v2
	v_mov_b32_e32 v157, v156
	v_cvt_pk_bf16_f32 v121, v18, v19
	v_cvt_pk_bf16_f32 v122, v20, v21
	v_cvt_pk_bf16_f32 v123, v22, v23
	v_cvt_pk_bf16_f32 v124, v24, v25
	v_cvt_pk_bf16_f32 v125, v26, v27
	v_cvt_pk_bf16_f32 v126, v28, v29
	v_cvt_pk_bf16_f32 v127, v30, v31
	v_cvt_pk_bf16_f32 v128, v32, v33
	v_cvt_pk_bf16_f32 v129, v34, v3
	v_mov_b32_e32 v3, v2
	v_mov_b32_e32 v4, v2
	v_mov_b32_e32 v5, v2
	v_mov_b32_e32 v6, v2
	v_mov_b32_e32 v7, v2
	v_mov_b32_e32 v8, v2
	v_mov_b32_e32 v9, v2
	v_mov_b32_e32 v10, v2
	v_mov_b32_e32 v11, v2
	v_mov_b32_e32 v12, v2
	v_mov_b32_e32 v13, v2
	v_mov_b32_e32 v14, v2
	v_mov_b32_e32 v15, v2
	v_mov_b64_e32 v[32:33], v[16:17]
	v_mov_b64_e32 v[48:49], v[16:17]
	v_permlane32_swap_b32_e32 v156, v157
	v_permlane32_swap_b32_e32 v114, v116
	v_permlane32_swap_b32_e32 v115, v117
	v_permlane32_swap_b32_e32 v118, v120
	v_permlane32_swap_b32_e32 v119, v121
	v_permlane32_swap_b32_e32 v122, v124
	v_permlane32_swap_b32_e32 v123, v125
	v_permlane32_swap_b32_e32 v126, v128
	v_permlane32_swap_b32_e32 v127, v129
	v_mov_b64_e32 v[30:31], v[14:15]
	v_mov_b64_e32 v[28:29], v[12:13]
	v_mov_b64_e32 v[26:27], v[10:11]
	v_mov_b64_e32 v[24:25], v[8:9]
	v_mov_b64_e32 v[22:23], v[6:7]
	v_mov_b64_e32 v[20:21], v[4:5]
	v_mov_b64_e32 v[18:19], v[2:3]
	v_mov_b64_e32 v[46:47], v[14:15]
	v_mov_b64_e32 v[44:45], v[12:13]
	v_mov_b64_e32 v[42:43], v[10:11]
	v_mov_b64_e32 v[40:41], v[8:9]
	v_mov_b64_e32 v[38:39], v[6:7]
	v_mov_b64_e32 v[36:37], v[4:5]
	v_mov_b64_e32 v[34:35], v[2:3]

.LBB0_391:
	s_nop 7
	v_max_f32_e32 v3, v99, v99
	v_max_f32_e32 v4, v98, v98
	v_max_f32_e32 v3, v4, v3
	v_max3_f32 v3, v3, v100, v101
	v_max3_f32 v3, v3, v102, v103
	v_max3_f32 v3, v3, v104, v105
	v_max3_f32 v3, v3, v106, v107
	v_max3_f32 v3, v3, v108, v109
	v_max3_f32 v3, v3, v110, v111
	v_max3_f32 v3, v3, v112, v113
	v_max3_f32 v3, v3, v82, v83
	v_max3_f32 v3, v3, v84, v85
	v_max3_f32 v3, v3, v86, v87
	v_max3_f32 v3, v3, v88, v89
	v_max3_f32 v3, v3, v90, v91
	v_max3_f32 v3, v3, v92, v93
	v_max3_f32 v3, v3, v94, v95
	v_max3_f32 v3, v3, v96, v97
	v_mov_b32_e32 v4, v3
	s_nop 1
	v_permlane32_swap_b32_e32 v3, v4
	v_max_f32_e32 v4, v4, v4
	v_max_f32_e32 v3, v3, v3
	v_max_f32_e32 v3, v3, v4
	v_sub_f32_e32 v4, v3, v232
	v_mul_f32_e32 v4, 0x3d93cd3a, v4
	v_cmp_ge_f32_e32 vcc, s96, v4
	v_max_f32_e32 v5, v232, v232
	s_cmp_eq_u64 vcc, exec
	v_max_f32_e32 v5, v5, v3
	s_cselect_b64 vcc, -1, 0
	v_sub_f32_e32 v3, v232, v5
	v_cndmask_b32_e32 v232, v5, v232, vcc
	v_mul_f32_e32 v4, 0xbdd53b94, v232
	v_fmamk_f32 v5, v98, 0x3dd53b94, v4
	v_fmamk_f32 v6, v99, 0x3dd53b94, v4
	v_exp_f32_e32 v5, v5
	v_fmamk_f32 v7, v100, 0x3dd53b94, v4
	v_exp_f32_e32 v6, v6
	v_fmamk_f32 v8, v101, 0x3dd53b94, v4
	v_exp_f32_e32 v7, v7
	v_fmamk_f32 v9, v102, 0x3dd53b94, v4
	v_fmamk_f32 v10, v103, 0x3dd53b94, v4
	v_fmamk_f32 v11, v104, 0x3dd53b94, v4
	v_fmamk_f32 v12, v105, 0x3dd53b94, v4
	v_fmamk_f32 v13, v106, 0x3dd53b94, v4
	v_fmamk_f32 v14, v107, 0x3dd53b94, v4
	v_fmamk_f32 v15, v108, 0x3dd53b94, v4
	v_fmamk_f32 v16, v109, 0x3dd53b94, v4
	v_fmamk_f32 v17, v110, 0x3dd53b94, v4
	v_fmamk_f32 v98, v111, 0x3dd53b94, v4
	v_fmamk_f32 v99, v112, 0x3dd53b94, v4
	v_fmamk_f32 v100, v113, 0x3dd53b94, v4
	v_fmamk_f32 v82, v82, 0x3dd53b94, v4
	v_fmamk_f32 v83, v83, 0x3dd53b94, v4
	v_fmamk_f32 v84, v84, 0x3dd53b94, v4
	v_fmamk_f32 v85, v85, 0x3dd53b94, v4
	v_fmamk_f32 v86, v86, 0x3dd53b94, v4
	v_fmamk_f32 v87, v87, 0x3dd53b94, v4
	v_fmamk_f32 v88, v88, 0x3dd53b94, v4
	v_fmamk_f32 v89, v89, 0x3dd53b94, v4
	v_fmamk_f32 v90, v90, 0x3dd53b94, v4
	v_fmamk_f32 v91, v91, 0x3dd53b94, v4
	v_fmamk_f32 v92, v92, 0x3dd53b94, v4
	v_fmamk_f32 v93, v93, 0x3dd53b94, v4
	v_fmamk_f32 v94, v94, 0x3dd53b94, v4
	v_fmamk_f32 v95, v95, 0x3dd53b94, v4
	v_fmamk_f32 v96, v96, 0x3dd53b94, v4
	v_fmac_f32_e32 v4, 0x3dd53b94, v97
	v_exp_f32_e32 v8, v8
	v_exp_f32_e32 v9, v9
	v_exp_f32_e32 v102, v4
	v_add_f32_e32 v4, 0, v5
	v_exp_f32_e32 v10, v10
	v_add_f32_e32 v4, v6, v4
	v_exp_f32_e32 v11, v11
	v_add_f32_e32 v4, v7, v4
	v_exp_f32_e32 v12, v12
	v_add_f32_e32 v4, v8, v4
	v_exp_f32_e32 v13, v13
	v_add_f32_e32 v4, v9, v4
	v_exp_f32_e32 v14, v14
	v_add_f32_e32 v4, v10, v4
	v_exp_f32_e32 v15, v15
	v_add_f32_e32 v4, v11, v4
	v_exp_f32_e32 v97, v16
	v_add_f32_e32 v4, v12, v4
	v_exp_f32_e32 v101, v17
	v_add_f32_e32 v4, v13, v4
	v_exp_f32_e32 v98, v98
	v_add_f32_e32 v4, v14, v4
	v_exp_f32_e32 v99, v99
	v_add_f32_e32 v4, v15, v4
	v_exp_f32_e32 v100, v100
	v_add_f32_e32 v4, v97, v4
	v_exp_f32_e32 v82, v82
	v_add_f32_e32 v4, v101, v4
	v_exp_f32_e32 v83, v83
	v_add_f32_e32 v4, v98, v4
	v_exp_f32_e32 v84, v84
	v_add_f32_e32 v4, v99, v4
	v_exp_f32_e32 v85, v85
	v_add_f32_e32 v4, v100, v4
	v_exp_f32_e32 v86, v86
	v_add_f32_e32 v4, v82, v4
	v_exp_f32_e32 v87, v87
	v_add_f32_e32 v4, v83, v4
	v_exp_f32_e32 v88, v88
	v_add_f32_e32 v4, v84, v4
	v_exp_f32_e32 v89, v89
	v_add_f32_e32 v4, v85, v4
	v_exp_f32_e32 v90, v90
	v_add_f32_e32 v4, v86, v4
	v_exp_f32_e32 v91, v91
	v_add_f32_e32 v4, v87, v4
	v_exp_f32_e32 v92, v92
	v_add_f32_e32 v4, v88, v4
	v_exp_f32_e32 v93, v93
	v_add_f32_e32 v4, v89, v4
	v_exp_f32_e32 v94, v94
	v_add_f32_e32 v4, v90, v4
	v_exp_f32_e32 v95, v95
	v_add_f32_e32 v4, v91, v4
	v_exp_f32_e32 v96, v96
	v_add_f32_e32 v4, v92, v4
	v_mul_f32_e32 v3, 0x3dd53b94, v3
	v_add_f32_e32 v4, v93, v4
	v_exp_f32_e32 v3, v3
	v_add_f32_e32 v4, v94, v4
	v_add_f32_e32 v4, v95, v4
	v_add_f32_e32 v4, v96, v4
	v_add_f32_e32 v16, v102, v4
	v_cndmask_b32_e64 v3, v3, 1.0, vcc
	v_mov_b32_e32 v17, v16
	v_cvt_pk_bf16_f32 v4, v5, v6
	v_cvt_pk_bf16_f32 v5, v7, v8
	v_cvt_pk_bf16_f32 v6, v9, v10
	v_cvt_pk_bf16_f32 v7, v11, v12
	v_cvt_pk_bf16_f32 v8, v13, v14
	v_cvt_pk_bf16_f32 v9, v15, v97
	v_cvt_pk_bf16_f32 v10, v101, v98
	v_cvt_pk_bf16_f32 v11, v99, v100
	v_cvt_pk_bf16_f32 v12, v82, v83
	v_cvt_pk_bf16_f32 v13, v84, v85
	v_cvt_pk_bf16_f32 v14, v86, v87
	v_cvt_pk_bf16_f32 v15, v88, v89
	v_cvt_pk_bf16_f32 v82, v90, v91
	v_cvt_pk_bf16_f32 v83, v92, v93
	v_cvt_pk_bf16_f32 v84, v94, v95
	v_cvt_pk_bf16_f32 v85, v96, v102
	s_nop 1
	v_permlane32_swap_b32_e32 v16, v17
	v_permlane32_swap_b32_e32 v4, v6
	v_permlane32_swap_b32_e32 v5, v7
	v_permlane32_swap_b32_e32 v8, v10
	v_permlane32_swap_b32_e32 v9, v11
	v_permlane32_swap_b32_e32 v12, v14
	v_permlane32_swap_b32_e32 v13, v15
	v_permlane32_swap_b32_e32 v82, v84
	v_permlane32_swap_b32_e32 v83, v85
	v_cmp_gt_f32_e32 vcc, 1.0, v3
	s_cbranch_vccz .LBB0_395
	s_and_saveexec_b64 s[8:9], s[6:7]
	ds_write_b32 v226, v3 offset:128
	s_or_b64 exec, exec, s[8:9]
	s_waitcnt lgkmcnt(0)
	ds_read_b128 v[86:89], v214 offset:224
	ds_read_b128 v[90:93], v214 offset:192
	ds_read_b128 v[94:97], v214 offset:160
	ds_read_b128 v[98:101], v214 offset:128
	s_waitcnt lgkmcnt(3)
	v_pk_mul_f32 v[80:81], v[80:81], v[88:89]
	s_waitcnt lgkmcnt(2)
	v_pk_mul_f32 v[76:77], v[76:77], v[92:93]
	s_waitcnt lgkmcnt(1)
	v_pk_mul_f32 v[72:73], v[72:73], v[96:97]
	s_waitcnt lgkmcnt(0)
	v_pk_mul_f32 v[68:69], v[68:69], v[100:101]
	v_pk_mul_f32 v[78:79], v[78:79], v[86:87]
	v_pk_mul_f32 v[74:75], v[74:75], v[90:91]
	v_pk_mul_f32 v[70:71], v[70:71], v[94:95]
	v_pk_mul_f32 v[66:67], v[66:67], v[98:99]
	v_pk_mul_f32 v[64:65], v[64:65], v[88:89]
	v_pk_mul_f32 v[60:61], v[60:61], v[92:93]
	v_pk_mul_f32 v[56:57], v[56:57], v[96:97]
	v_pk_mul_f32 v[52:53], v[52:53], v[100:101]
	v_pk_mul_f32 v[62:63], v[62:63], v[86:87]
	v_pk_mul_f32 v[58:59], v[58:59], v[90:91]
	v_pk_mul_f32 v[54:55], v[54:55], v[94:95]
	v_pk_mul_f32 v[50:51], v[50:51], v[98:99]
	v_pk_mul_f32 v[48:49], v[48:49], v[88:89]
	v_pk_mul_f32 v[44:45], v[44:45], v[92:93]
	v_pk_mul_f32 v[40:41], v[40:41], v[96:97]
	v_pk_mul_f32 v[36:37], v[36:37], v[100:101]
	v_pk_mul_f32 v[46:47], v[46:47], v[86:87]
	v_pk_mul_f32 v[42:43], v[42:43], v[90:91]
	v_pk_mul_f32 v[38:39], v[38:39], v[94:95]
	v_pk_mul_f32 v[34:35], v[34:35], v[98:99]
	v_pk_mul_f32 v[32:33], v[32:33], v[88:89]
	v_pk_mul_f32 v[28:29], v[28:29], v[92:93]
	v_pk_mul_f32 v[24:25], v[24:25], v[96:97]
	v_pk_mul_f32 v[20:21], v[20:21], v[100:101]
	v_pk_mul_f32 v[30:31], v[30:31], v[86:87]
	v_pk_mul_f32 v[26:27], v[26:27], v[90:91]
	v_pk_mul_f32 v[22:23], v[22:23], v[94:95]
	v_pk_mul_f32 v[18:19], v[18:19], v[98:99]
